# stack6 + attention waveskew: waves 0-3 run the scale+exp block before the pre-write barrier, waves 4-7 after the post-write barrier; first barrier moved next to the K/V LDS writes
# speedup vs baseline: 1.0054x; 1.0054x over previous
.LBB0_518:
	ds_read_b128 v[66:69], v213 offset:49152
	ds_read_b128 v[70:73], v213 offset:57344
	ds_read_b128 v[226:229], v214 offset:49152
	ds_read_b128 v[230:233], v214 offset:57344
	v_add_f32_e32 v162, 0, v177
	v_add_f32_e32 v162, v191, v162
	s_waitcnt lgkmcnt(3)
	v_mfma_f32_32x32x16_bf16 v[82:97], v[66:69], v[126:129], 0
	v_add_f32_e32 v162, v163, v162
	v_add_f32_e32 v162, v190, v162
	v_add_f32_e32 v162, v164, v162
	v_add_f32_e32 v162, v176, v162
	v_add_f32_e32 v162, v165, v162
	v_add_f32_e32 v162, v175, v162
	v_add_f32_e32 v162, v166, v162
	s_waitcnt lgkmcnt(2)
	v_mfma_f32_32x32x16_bf16 v[66:81], v[70:73], v[126:129], 0
	v_add_f32_e32 v162, v173, v162
	v_add_f32_e32 v162, v167, v162
	v_add_f32_e32 v162, v172, v162
	v_exp_f32_e32 v158, v158
	v_add_f32_e32 v162, v168, v162
	v_exp_f32_e32 v159, v159
	v_add_f32_e32 v162, v170, v162
	s_waitcnt lgkmcnt(1)
	v_mfma_f32_32x32x16_bf16 v[82:97], v[226:229], v[122:125], v[82:97]
	v_exp_f32_e32 v156, v156
	v_add_f32_e32 v162, v169, v162
	v_exp_f32_e32 v157, v157
	v_add_f32_e32 v162, v171, v162
	v_exp_f32_e32 v152, v152
	v_add_f32_e32 v162, v158, v162
	v_exp_f32_e32 v153, v153
	s_waitcnt lgkmcnt(0)
	v_mfma_f32_32x32x16_bf16 v[66:81], v[230:233], v[122:125], v[66:81]
	ds_read_b128 v[226:229], v215 offset:49152
	ds_read_b128 v[230:233], v215 offset:57344
	v_add_f32_e32 v162, v159, v162
	v_exp_f32_e32 v150, v150
	v_add_f32_e32 v162, v156, v162
	v_exp_f32_e32 v151, v151
	v_add_f32_e32 v162, v157, v162
	v_exp_f32_e32 v146, v146
	s_waitcnt lgkmcnt(1)
	v_mfma_f32_32x32x16_bf16 v[82:97], v[226:229], v[118:121], v[82:97]
	v_add_f32_e32 v162, v152, v162
	v_exp_f32_e32 v147, v147
	v_add_f32_e32 v162, v153, v162
	v_exp_f32_e32 v160, v160
	v_add_f32_e32 v162, v150, v162
	v_exp_f32_e32 v161, v161
	v_add_f32_e32 v162, v151, v162
	s_waitcnt lgkmcnt(0)
	v_mfma_f32_32x32x16_bf16 v[66:81], v[230:233], v[118:121], v[66:81]
	ds_read_b128 v[226:229], v216 offset:49152
	ds_read_b128 v[230:233], v216 offset:57344
	v_exp_f32_e32 v154, v154
	v_add_f32_e32 v162, v146, v162
	v_exp_f32_e32 v155, v155
	v_add_f32_e32 v162, v147, v162
	v_exp_f32_e32 v148, v148
	v_add_f32_e32 v162, v160, v162
	s_waitcnt lgkmcnt(1)
	v_mfma_f32_32x32x16_bf16 v[82:97], v[226:229], v[114:117], v[82:97]
	v_exp_f32_e32 v149, v149
	v_add_f32_e32 v162, v161, v162
	v_add_f32_e32 v162, v154, v162
	v_add_f32_e32 v162, v155, v162
	v_add_f32_e32 v162, v148, v162
	v_add_f32_e32 v225, v149, v162
	s_waitcnt lgkmcnt(0)
	v_mfma_f32_32x32x16_bf16 v[66:81], v[230:233], v[114:117], v[66:81]
	ds_read_b128 v[226:229], v217 offset:49152
	ds_read_b128 v[230:233], v217 offset:57344
	s_waitcnt lgkmcnt(1)
	v_mfma_f32_32x32x16_bf16 v[82:97], v[226:229], v[110:113], v[82:97]
	s_waitcnt lgkmcnt(0)
	v_mfma_f32_32x32x16_bf16 v[66:81], v[230:233], v[110:113], v[66:81]
	ds_read_b128 v[226:229], v218 offset:49152
	ds_read_b128 v[230:233], v218 offset:57344
	s_waitcnt lgkmcnt(1)
	v_mfma_f32_32x32x16_bf16 v[82:97], v[226:229], v[106:109], v[82:97]
	s_waitcnt lgkmcnt(0)
	v_mfma_f32_32x32x16_bf16 v[66:81], v[230:233], v[106:109], v[66:81]
	ds_read_b128 v[226:229], v219 offset:49152
	ds_read_b128 v[230:233], v219 offset:57344
	s_waitcnt lgkmcnt(1)
	v_mfma_f32_32x32x16_bf16 v[82:97], v[226:229], v[102:105], v[82:97]
	s_waitcnt lgkmcnt(0)
	v_mfma_f32_32x32x16_bf16 v[66:81], v[230:233], v[102:105], v[66:81]
	ds_read_b128 v[226:229], v220 offset:49152
	ds_read_b128 v[230:233], v220 offset:57344
	v_cvt_pk_bf16_f32 v162, v177, v191
	v_cvt_pk_bf16_f32 v163, v163, v190
	v_cvt_pk_bf16_f32 v164, v164, v176
	v_cvt_pk_bf16_f32 v165, v165, v175
	v_cvt_pk_bf16_f32 v166, v166, v173
	v_cvt_pk_bf16_f32 v167, v167, v172
	s_waitcnt lgkmcnt(1)
	v_mfma_f32_32x32x16_bf16 v[82:97], v[226:229], v[98:101], v[82:97]
	v_mov_b32_e32 v226, v225
	s_nop 1
	v_permlane32_swap_b32_e32 v225, v226
	v_permlane32_swap_b32_e32 v162, v164
	v_cvt_pk_bf16_f32 v168, v168, v170
	v_cvt_pk_bf16_f32 v169, v169, v171
	s_waitcnt lgkmcnt(0)
	v_mfma_f32_32x32x16_bf16 v[66:81], v[230:233], v[98:101], v[66:81]
	v_cvt_pk_bf16_f32 v170, v158, v159
	v_cvt_pk_bf16_f32 v171, v156, v157
	v_cvt_pk_bf16_f32 v172, v152, v153
	v_cvt_pk_bf16_f32 v173, v150, v151
	v_cvt_pk_bf16_f32 v228, v146, v147
	v_cvt_pk_bf16_f32 v229, v160, v161
	v_cvt_pk_bf16_f32 v230, v154, v155
	v_cvt_pk_bf16_f32 v231, v148, v149
	v_permlane32_swap_b32_e32 v163, v165
	v_permlane32_swap_b32_e32 v166, v168
	v_permlane32_swap_b32_e32 v167, v169
	v_permlane32_swap_b32_e32 v170, v172
	v_permlane32_swap_b32_e32 v171, v173
	v_permlane32_swap_b32_e32 v228, v230
	v_permlane32_swap_b32_e32 v229, v231
	v_lshl_add_u64 v[192:193], v[186:187], 0, s[36:37]
	v_add_co_u32_e32 v146, vcc, s17, v192
	v_lshl_add_u64 v[190:191], v[188:189], 0, s[36:37]
	s_nop 0
	v_addc_co_u32_e32 v147, vcc, 0, v193, vcc
	v_add_co_u32_e32 v150, vcc, s20, v192
	s_nop 1
	v_addc_co_u32_e32 v151, vcc, 0, v193, vcc
	v_add_co_u32_e32 v154, vcc, s17, v190
	global_load_dwordx4 v[146:149], v[146:147], off
	s_nop 0
	global_load_dwordx4 v[150:153], v[150:151], off
	v_addc_co_u32_e32 v155, vcc, 0, v191, vcc
	v_add_co_u32_e32 v158, vcc, s20, v190
	s_nop 1
	v_addc_co_u32_e32 v159, vcc, 0, v191, vcc
	global_load_dwordx4 v[154:157], v[154:155], off
	s_nop 0
	global_load_dwordx4 v[158:161], v[158:159], off
	ds_read_b64_tr_b16 v[232:233], v194 offset:0
	ds_read_b64_tr_b16 v[234:235], v194 offset:0x800
	ds_read_b64_tr_b16 v[236:237], v194 offset:0x1000
	ds_read_b64_tr_b16 v[238:239], v194 offset:0x1800
	ds_read_b64_tr_b16 v[240:241], v194 offset:0x2000
	ds_read_b64_tr_b16 v[242:243], v194 offset:0x2800
	ds_read_b64_tr_b16 v[244:245], v194 offset:0x3000
	ds_read_b64_tr_b16 v[246:247], v194 offset:0x3800
	s_waitcnt lgkmcnt(0)
	s_nop 0
	v_mfma_f32_32x32x16_bf16 v[2:17], v[162:165], v[232:235], v[2:17]
	ds_read_b64_tr_b16 v[232:233], v194 offset:0x200
	ds_read_b64_tr_b16 v[234:235], v194 offset:0xa00
	v_mfma_f32_32x32x16_bf16 v[2:17], v[166:169], v[236:239], v[2:17]
	ds_read_b64_tr_b16 v[236:237], v194 offset:0x1200
	ds_read_b64_tr_b16 v[238:239], v194 offset:0x1a00
	v_mfma_f32_32x32x16_bf16 v[2:17], v[170:173], v[240:243], v[2:17]
	ds_read_b64_tr_b16 v[240:241], v194 offset:0x2200
	ds_read_b64_tr_b16 v[242:243], v194 offset:0x2a00
	ds_read_b64_tr_b16 v[248:249], v194 offset:0x3200
	ds_read_b64_tr_b16 v[250:251], v194 offset:0x3a00
	s_waitcnt lgkmcnt(0)
	v_mfma_f32_32x32x16_bf16 v[2:17], v[228:231], v[244:247], v[2:17]
	v_mfma_f32_32x32x16_bf16 v[50:65], v[162:165], v[232:235], v[50:65]
	ds_read_b64_tr_b16 v[232:233], v194 offset:0x400
	ds_read_b64_tr_b16 v[234:235], v194 offset:0xc00
	v_mfma_f32_32x32x16_bf16 v[50:65], v[166:169], v[236:239], v[50:65]
	ds_read_b64_tr_b16 v[236:237], v194 offset:0x1400
	ds_read_b64_tr_b16 v[238:239], v194 offset:0x1c00
	v_mfma_f32_32x32x16_bf16 v[50:65], v[170:173], v[240:243], v[50:65]
	ds_read_b64_tr_b16 v[240:241], v194 offset:0x2400
	ds_read_b64_tr_b16 v[242:243], v194 offset:0x2c00
	ds_read_b64_tr_b16 v[244:245], v194 offset:0x3400
	ds_read_b64_tr_b16 v[246:247], v194 offset:0x3c00
	s_waitcnt lgkmcnt(0)
	v_mfma_f32_32x32x16_bf16 v[50:65], v[228:231], v[248:251], v[50:65]
	v_mfma_f32_32x32x16_bf16 v[34:49], v[162:165], v[232:235], v[34:49]
	ds_read_b64_tr_b16 v[232:233], v194 offset:0x600
	ds_read_b64_tr_b16 v[234:235], v194 offset:0xe00
	v_mfma_f32_32x32x16_bf16 v[34:49], v[166:169], v[236:239], v[34:49]
	ds_read_b64_tr_b16 v[236:237], v194 offset:0x1600
	ds_read_b64_tr_b16 v[238:239], v194 offset:0x1e00
	v_mfma_f32_32x32x16_bf16 v[34:49], v[170:173], v[240:243], v[34:49]
	ds_read_b64_tr_b16 v[240:241], v194 offset:0x2600
	ds_read_b64_tr_b16 v[242:243], v194 offset:0x2e00
	ds_read_b64_tr_b16 v[248:249], v194 offset:0x3600
	ds_read_b64_tr_b16 v[250:251], v194 offset:0x3e00
	s_waitcnt lgkmcnt(0)
	v_mfma_f32_32x32x16_bf16 v[34:49], v[228:231], v[244:247], v[34:49]
	v_mfma_f32_32x32x16_bf16 v[18:33], v[162:165], v[232:235], v[18:33]
	v_max3_f32 v175, v82, v83, v84
	v_max3_f32 v176, v66, v67, v68
	v_max_f32_e32 v164, v81, v81
	v_max3_f32 v175, v175, v85, v86
	v_max3_f32 v176, v176, v69, v70
	v_max_f32_e32 v165, v97, v97
	v_max3_f32 v162, v176, v71, v72
	v_mfma_f32_32x32x16_bf16 v[18:33], v[166:169], v[236:239], v[18:33]
	v_max3_f32 v175, v175, v87, v88
	v_max3_f32 v162, v162, v73, v74
	v_max_f32_e32 v164, v165, v164
	v_max3_f32 v163, v175, v89, v90
	v_max3_f32 v162, v162, v75, v76
	s_nop 0
	v_max3_f32 v163, v163, v91, v92
	v_mfma_f32_32x32x16_bf16 v[18:33], v[170:173], v[240:243], v[18:33]
	v_max3_f32 v163, v163, v93, v94
	v_max3_f32 v162, v162, v77, v78
	v_max3_f32 v163, v163, v95, v96
	v_max3_f32 v162, v162, v79, v80
	s_nop 0
	v_max3_f32 v162, v163, v162, v164
	v_max_f32_e32 v164, v174, v174
	v_mov_b32_e32 v163, v162
	s_nop 1
	v_permlane32_swap_b32_e32 v162, v163
	v_max_f32_e32 v163, v163, v163
	v_max_f32_e32 v162, v162, v162
	v_max_f32_e32 v162, v162, v163
	v_sub_f32_e32 v163, v162, v174
	v_max_f32_e32 v162, v164, v162
	v_mfma_f32_32x32x16_bf16 v[18:33], v[228:231], v[248:251], v[18:33]
	v_sub_f32_e32 v164, v174, v162
	v_mul_f32_e32 v164, 0x3e0293ee, v164
	v_exp_f32_e32 v164, v164
	v_cmp_ge_f32_e32 vcc, s16, v163
	s_cmp_eq_u64 vcc, exec
	s_cselect_b64 s[6:7], -1, 0
	s_waitcnt vmcnt(4)
	v_cndmask_b32_e64 v227, v164, 1.0, s[6:7]
	v_cmp_gt_f32_e32 vcc, 1.0, v227
	s_bitcmp1_b32 s29, 10
	s_cbranch_scc1 .Lattn_xs1
	v_cndmask_b32_e64 v228, v162, v174, s[6:7]
	v_mul_f32_e32 v229, 0xbe0293ee, v228
	v_fmamk_f32 v82, v82, 0x3e0293ee, v229
	v_fmamk_f32 v83, v83, 0x3e0293ee, v229
	v_fmamk_f32 v84, v84, 0x3e0293ee, v229
	v_fmamk_f32 v85, v85, 0x3e0293ee, v229
	v_fmamk_f32 v86, v86, 0x3e0293ee, v229
	v_fmamk_f32 v87, v87, 0x3e0293ee, v229
	v_fmamk_f32 v88, v88, 0x3e0293ee, v229
	v_fmamk_f32 v89, v89, 0x3e0293ee, v229
	v_fmamk_f32 v90, v90, 0x3e0293ee, v229
	v_fmamk_f32 v91, v91, 0x3e0293ee, v229
	v_fmamk_f32 v92, v92, 0x3e0293ee, v229
	v_fmamk_f32 v93, v93, 0x3e0293ee, v229
	v_fmamk_f32 v94, v94, 0x3e0293ee, v229
	v_fmamk_f32 v95, v95, 0x3e0293ee, v229
	v_fmamk_f32 v96, v96, 0x3e0293ee, v229
	v_fmamk_f32 v97, v97, 0x3e0293ee, v229
	v_exp_f32_e32 v166, v82
	v_exp_f32_e32 v177, v83
	v_exp_f32_e32 v167, v84
	v_exp_f32_e32 v176, v85
	v_exp_f32_e32 v168, v86
	v_exp_f32_e32 v175, v87
	v_exp_f32_e32 v169, v88
	v_exp_f32_e32 v174, v89
	v_exp_f32_e32 v162, v90
	v_exp_f32_e32 v173, v91
	v_exp_f32_e32 v163, v92
	v_exp_f32_e32 v172, v93
	v_exp_f32_e32 v164, v94
	v_exp_f32_e32 v171, v95
	v_exp_f32_e32 v165, v96
	v_exp_f32_e32 v170, v97
	v_fmamk_f32 v238, v66, 0x3e0293ee, v229
	v_fmamk_f32 v239, v67, 0x3e0293ee, v229
	v_fmamk_f32 v240, v68, 0x3e0293ee, v229
	v_fmamk_f32 v241, v69, 0x3e0293ee, v229
	v_fmamk_f32 v242, v70, 0x3e0293ee, v229
	v_fmamk_f32 v231, v71, 0x3e0293ee, v229
	v_fmamk_f32 v232, v72, 0x3e0293ee, v229
	v_fmamk_f32 v233, v73, 0x3e0293ee, v229
	v_fmamk_f32 v234, v74, 0x3e0293ee, v229
	v_fmamk_f32 v235, v75, 0x3e0293ee, v229
	v_fmamk_f32 v236, v76, 0x3e0293ee, v229
	v_fmamk_f32 v237, v77, 0x3e0293ee, v229
	v_fmamk_f32 v230, v78, 0x3e0293ee, v229
	v_fmamk_f32 v243, v79, 0x3e0293ee, v229
	v_fmamk_f32 v244, v80, 0x3e0293ee, v229
	v_fmac_f32_e32 v229, 0x3e0293ee, v81
.Lattn_xs1:
	s_barrier
	s_waitcnt vmcnt(4)
	ds_write_b128 v209, v[130:133]
	ds_write_b128 v210, v[134:137]
	ds_write_b128 v211, v[138:141] offset:32768
	ds_write_b128 v212, v[142:145] offset:32768
	s_cbranch_vccz .LBB0_522
	s_bitcmp1_b32 s29, 10
	s_cbranch_scc0 .Lattn_rescx1
	s_and_saveexec_b64 s[38:39], s[4:5]
	ds_write_b32 v222, v227 offset:128
	s_or_b64 exec, exec, s[38:39]
	s_waitcnt lgkmcnt(0)
	v_add_u32_e32 v163, s29, v195
	ds_read_b128 v[164:167], v163 offset:224
	ds_read_b128 v[168:171], v163 offset:192
	ds_read_b128 v[228:231], v163 offset:160
	ds_read_b128 v[232:235], v163 offset:128
	s_waitcnt lgkmcnt(3)
	v_pk_mul_f32 v[14:15], v[14:15], v[164:165]
	s_waitcnt lgkmcnt(2)
	v_pk_mul_f32 v[10:11], v[10:11], v[168:169]
	s_waitcnt lgkmcnt(1)
	v_pk_mul_f32 v[6:7], v[6:7], v[228:229]
	v_pk_mul_f32 v[16:17], v[16:17], v[166:167]
	v_pk_mul_f32 v[12:13], v[12:13], v[170:171]
	v_pk_mul_f32 v[8:9], v[8:9], v[230:231]
	s_waitcnt lgkmcnt(0)
	v_pk_mul_f32 v[4:5], v[4:5], v[234:235]
	v_pk_mul_f32 v[2:3], v[2:3], v[232:233]
	v_pk_mul_f32 v[62:63], v[62:63], v[164:165]
	v_pk_mul_f32 v[58:59], v[58:59], v[168:169]
	v_pk_mul_f32 v[54:55], v[54:55], v[228:229]
	v_pk_mul_f32 v[64:65], v[64:65], v[166:167]
	v_pk_mul_f32 v[60:61], v[60:61], v[170:171]
	v_pk_mul_f32 v[56:57], v[56:57], v[230:231]
	v_pk_mul_f32 v[52:53], v[52:53], v[234:235]
	v_pk_mul_f32 v[50:51], v[50:51], v[232:233]
	v_pk_mul_f32 v[46:47], v[46:47], v[164:165]
	v_pk_mul_f32 v[42:43], v[42:43], v[168:169]
	v_pk_mul_f32 v[38:39], v[38:39], v[228:229]
	v_pk_mul_f32 v[48:49], v[48:49], v[166:167]
	v_pk_mul_f32 v[44:45], v[44:45], v[170:171]
	v_pk_mul_f32 v[40:41], v[40:41], v[230:231]
	v_pk_mul_f32 v[36:37], v[36:37], v[234:235]
	v_pk_mul_f32 v[34:35], v[34:35], v[232:233]
	v_pk_mul_f32 v[30:31], v[30:31], v[164:165]
	v_pk_mul_f32 v[26:27], v[26:27], v[168:169]
	v_pk_mul_f32 v[22:23], v[22:23], v[228:229]
	v_pk_mul_f32 v[32:33], v[32:33], v[166:167]
	v_pk_mul_f32 v[28:29], v[28:29], v[170:171]
	v_pk_mul_f32 v[24:25], v[24:25], v[230:231]
	v_pk_mul_f32 v[20:21], v[20:21], v[234:235]
	v_pk_mul_f32 v[18:19], v[18:19], v[232:233]
.LBB0_522:
	s_waitcnt lgkmcnt(0)
	s_barrier
	s_bitcmp1_b32 s29, 10
	s_cbranch_scc0 .Lattn_ys1
	v_cndmask_b32_e64 v228, v162, v174, s[6:7]
	v_mul_f32_e32 v229, 0xbe0293ee, v228
	v_fmamk_f32 v82, v82, 0x3e0293ee, v229
	v_fmamk_f32 v83, v83, 0x3e0293ee, v229
	v_fmamk_f32 v84, v84, 0x3e0293ee, v229
	v_fmamk_f32 v85, v85, 0x3e0293ee, v229
	v_fmamk_f32 v86, v86, 0x3e0293ee, v229
	v_fmamk_f32 v87, v87, 0x3e0293ee, v229
	v_fmamk_f32 v88, v88, 0x3e0293ee, v229
	v_fmamk_f32 v89, v89, 0x3e0293ee, v229
	v_fmamk_f32 v90, v90, 0x3e0293ee, v229
	v_fmamk_f32 v91, v91, 0x3e0293ee, v229
	v_fmamk_f32 v92, v92, 0x3e0293ee, v229
	v_fmamk_f32 v93, v93, 0x3e0293ee, v229
	v_fmamk_f32 v94, v94, 0x3e0293ee, v229
	v_fmamk_f32 v95, v95, 0x3e0293ee, v229
	v_fmamk_f32 v96, v96, 0x3e0293ee, v229
	v_fmamk_f32 v97, v97, 0x3e0293ee, v229
	v_exp_f32_e32 v166, v82
	v_exp_f32_e32 v177, v83
	v_exp_f32_e32 v167, v84
	v_exp_f32_e32 v176, v85
	v_exp_f32_e32 v168, v86
	v_exp_f32_e32 v175, v87
	v_exp_f32_e32 v169, v88
	v_exp_f32_e32 v174, v89
	v_exp_f32_e32 v162, v90
	v_exp_f32_e32 v173, v91
	v_exp_f32_e32 v163, v92
	v_exp_f32_e32 v172, v93
	v_exp_f32_e32 v164, v94
	v_exp_f32_e32 v171, v95
	v_exp_f32_e32 v165, v96
	v_exp_f32_e32 v170, v97
	v_fmamk_f32 v238, v66, 0x3e0293ee, v229
	v_fmamk_f32 v239, v67, 0x3e0293ee, v229
	v_fmamk_f32 v240, v68, 0x3e0293ee, v229
	v_fmamk_f32 v241, v69, 0x3e0293ee, v229
	v_fmamk_f32 v242, v70, 0x3e0293ee, v229
	v_fmamk_f32 v231, v71, 0x3e0293ee, v229
	v_fmamk_f32 v232, v72, 0x3e0293ee, v229
	v_fmamk_f32 v233, v73, 0x3e0293ee, v229
	v_fmamk_f32 v234, v74, 0x3e0293ee, v229
	v_fmamk_f32 v235, v75, 0x3e0293ee, v229
	v_fmamk_f32 v236, v76, 0x3e0293ee, v229
	v_fmamk_f32 v237, v77, 0x3e0293ee, v229
	v_fmamk_f32 v230, v78, 0x3e0293ee, v229
	v_fmamk_f32 v243, v79, 0x3e0293ee, v229
	v_fmamk_f32 v244, v80, 0x3e0293ee, v229
	v_fmac_f32_e32 v229, 0x3e0293ee, v81
.Lattn_ys1:
	ds_read_b128 v[66:69], v213 offset:32768
	ds_read_b128 v[70:73], v213 offset:40960
	ds_read_b128 v[246:249], v214 offset:32768
	ds_read_b128 v[250:253], v214 offset:40960
	v_exp_f32_e32 v238, v238
	v_exp_f32_e32 v239, v239
	s_waitcnt lgkmcnt(3)
	v_mfma_f32_32x32x16_bf16 v[82:97], v[66:69], v[126:129], 0
	v_exp_f32_e32 v240, v240
	v_exp_f32_e32 v241, v241
	v_exp_f32_e32 v242, v242
	v_exp_f32_e32 v231, v231
	v_exp_f32_e32 v232, v232
	v_exp_f32_e32 v233, v233
	v_exp_f32_e32 v234, v234
	s_waitcnt lgkmcnt(2)
	v_mfma_f32_32x32x16_bf16 v[66:81], v[70:73], v[126:129], 0
	v_exp_f32_e32 v235, v235
	v_exp_f32_e32 v236, v236
	v_exp_f32_e32 v237, v237
	v_exp_f32_e32 v245, v230
	v_exp_f32_e32 v243, v243
	v_exp_f32_e32 v244, v244
	s_waitcnt lgkmcnt(1)
	v_mfma_f32_32x32x16_bf16 v[82:97], v[246:249], v[122:125], v[82:97]
	s_waitcnt lgkmcnt(0)
	v_mfma_f32_32x32x16_bf16 v[66:81], v[250:253], v[122:125], v[66:81]
	ds_read_b128 v[246:249], v215 offset:32768
	ds_read_b128 v[250:253], v215 offset:40960
	s_waitcnt lgkmcnt(1)
	v_mfma_f32_32x32x16_bf16 v[82:97], v[246:249], v[118:121], v[82:97]
	s_waitcnt lgkmcnt(0)
	v_mfma_f32_32x32x16_bf16 v[66:81], v[250:253], v[118:121], v[66:81]
	ds_read_b128 v[246:249], v216 offset:32768
	ds_read_b128 v[250:253], v216 offset:40960
	s_waitcnt lgkmcnt(1)
	v_mfma_f32_32x32x16_bf16 v[82:97], v[246:249], v[114:117], v[82:97]
	s_waitcnt lgkmcnt(0)
	v_mfma_f32_32x32x16_bf16 v[66:81], v[250:253], v[114:117], v[66:81]
	ds_read_b128 v[246:249], v217 offset:32768
	ds_read_b128 v[250:253], v217 offset:40960
	s_waitcnt lgkmcnt(1)
	v_mfma_f32_32x32x16_bf16 v[82:97], v[246:249], v[110:113], v[82:97]
	s_waitcnt lgkmcnt(0)
	v_mfma_f32_32x32x16_bf16 v[66:81], v[250:253], v[110:113], v[66:81]
	ds_read_b128 v[246:249], v218 offset:32768
	ds_read_b128 v[250:253], v218 offset:40960
	s_waitcnt lgkmcnt(1)
	v_mfma_f32_32x32x16_bf16 v[82:97], v[246:249], v[106:109], v[82:97]
	s_waitcnt lgkmcnt(0)
	v_mfma_f32_32x32x16_bf16 v[66:81], v[250:253], v[106:109], v[66:81]
	ds_read_b128 v[246:249], v219 offset:32768
	ds_read_b128 v[250:253], v219 offset:40960
	s_waitcnt lgkmcnt(1)
	v_mfma_f32_32x32x16_bf16 v[82:97], v[246:249], v[102:105], v[82:97]
	s_waitcnt lgkmcnt(0)
	v_mfma_f32_32x32x16_bf16 v[66:81], v[250:253], v[102:105], v[66:81]
	ds_read_b128 v[246:249], v220 offset:32768
	ds_read_b128 v[250:253], v220 offset:40960
	s_waitcnt lgkmcnt(1)
	v_mfma_f32_32x32x16_bf16 v[82:97], v[246:249], v[98:101], v[82:97]
	v_exp_f32_e32 v246, v229
	v_add_f32_e32 v229, 0, v166
	v_add_f32_e32 v229, v177, v229
	v_add_f32_e32 v229, v167, v229
	v_add_f32_e32 v229, v176, v229
	v_add_f32_e32 v229, v168, v229
	v_add_f32_e32 v229, v175, v229
	v_add_f32_e32 v229, v169, v229
	v_add_f32_e32 v229, v174, v229
	v_add_f32_e32 v229, v162, v229
	v_add_f32_e32 v229, v173, v229
	v_add_f32_e32 v229, v163, v229
	v_add_f32_e32 v229, v172, v229
	v_add_f32_e32 v229, v164, v229
	v_add_f32_e32 v229, v171, v229
	v_add_f32_e32 v229, v165, v229
	v_add_f32_e32 v229, v170, v229
	v_add_f32_e32 v229, v238, v229
	v_add_f32_e32 v229, v239, v229
	v_add_f32_e32 v229, v240, v229
	v_add_f32_e32 v229, v241, v229
	v_add_f32_e32 v229, v242, v229
	v_add_f32_e32 v229, v231, v229
	v_add_f32_e32 v229, v232, v229
	v_add_f32_e32 v229, v233, v229
	v_add_f32_e32 v229, v234, v229
	v_add_f32_e32 v229, v235, v229
	s_waitcnt lgkmcnt(0)
	v_mfma_f32_32x32x16_bf16 v[66:81], v[250:253], v[98:101], v[66:81]
	v_add_f32_e32 v229, v236, v229
	v_add_f32_e32 v229, v237, v229
	v_add_f32_e32 v229, v245, v229
	v_add_f32_e32 v229, v243, v229
	v_add_f32_e32 v229, v244, v229
	v_add_f32_e32 v229, v246, v229
	v_mov_b32_e32 v230, v229
	v_cvt_pk_bf16_f32 v166, v166, v177
	v_cvt_pk_bf16_f32 v167, v167, v176
	v_cvt_pk_bf16_f32 v168, v168, v175
	v_cvt_pk_bf16_f32 v169, v169, v174
	v_cvt_pk_bf16_f32 v162, v162, v173
	v_cvt_pk_bf16_f32 v163, v163, v172
	v_cvt_pk_bf16_f32 v164, v164, v171
	v_cvt_pk_bf16_f32 v165, v165, v170
	v_cvt_pk_bf16_f32 v170, v238, v239
	v_cvt_pk_bf16_f32 v171, v240, v241
	v_cvt_pk_bf16_f32 v172, v242, v231
	v_cvt_pk_bf16_f32 v173, v232, v233
	v_cvt_pk_bf16_f32 v174, v234, v235
	v_cvt_pk_bf16_f32 v175, v236, v237
	v_cvt_pk_bf16_f32 v176, v245, v243
	v_cvt_pk_bf16_f32 v177, v244, v246
	s_nop 1
	v_permlane32_swap_b32_e32 v229, v230
	v_permlane32_swap_b32_e32 v166, v168
	v_permlane32_swap_b32_e32 v167, v169
	v_permlane32_swap_b32_e32 v162, v164
	v_permlane32_swap_b32_e32 v163, v165
	v_permlane32_swap_b32_e32 v170, v172
	v_permlane32_swap_b32_e32 v171, v173
	v_permlane32_swap_b32_e32 v174, v176
	v_permlane32_swap_b32_e32 v175, v177
	s_cmp_ge_u32 s30, s31
	s_cselect_b64 s[38:39], -1, 0
	s_and_b64 vcc, exec, s[38:39]
	s_cbranch_vccnz .LBB0_524
	v_add_co_u32_e32 v130, vcc, 0x40000, v192
	s_nop 1
	v_addc_co_u32_e32 v131, vcc, 0, v193, vcc
	v_add_co_u32_e32 v134, vcc, 0x48000, v192
	s_nop 1
	v_addc_co_u32_e32 v135, vcc, 0, v193, vcc
	v_add_co_u32_e32 v138, vcc, 0x40000, v190
	global_load_dwordx4 v[130:133], v[130:131], off
	s_nop 0
	global_load_dwordx4 v[134:137], v[134:135], off
	v_addc_co_u32_e32 v139, vcc, 0, v191, vcc
	v_add_co_u32_e32 v142, vcc, 0x48000, v190
	s_nop 1
	v_addc_co_u32_e32 v143, vcc, 0, v191, vcc
	global_load_dwordx4 v[138:141], v[138:139], off
	s_nop 0
	global_load_dwordx4 v[142:145], v[142:143], off
.LBB0_524:
	ds_read_b64_tr_b16 v[190:191], v196 offset:0
	ds_read_b64_tr_b16 v[192:193], v196 offset:0x800
	ds_read_b64_tr_b16 v[232:233], v196 offset:0x1000
	ds_read_b64_tr_b16 v[234:235], v196 offset:0x1800
	ds_read_b64_tr_b16 v[236:237], v196 offset:0x2000
	ds_read_b64_tr_b16 v[238:239], v196 offset:0x2800
	ds_read_b64_tr_b16 v[240:241], v196 offset:0x3000
	ds_read_b64_tr_b16 v[242:243], v196 offset:0x3800
	s_waitcnt lgkmcnt(0)
	s_nop 0
	v_mfma_f32_32x32x16_bf16 v[2:17], v[166:169], v[190:193], v[2:17]
	ds_read_b64_tr_b16 v[190:191], v196 offset:0x200
	ds_read_b64_tr_b16 v[192:193], v196 offset:0xa00
	v_mfma_f32_32x32x16_bf16 v[2:17], v[162:165], v[232:235], v[2:17]
	ds_read_b64_tr_b16 v[232:233], v196 offset:0x1200
	ds_read_b64_tr_b16 v[234:235], v196 offset:0x1a00
	v_mfma_f32_32x32x16_bf16 v[2:17], v[170:173], v[236:239], v[2:17]
	ds_read_b64_tr_b16 v[236:237], v196 offset:0x2200
	ds_read_b64_tr_b16 v[238:239], v196 offset:0x2a00
	ds_read_b64_tr_b16 v[244:245], v196 offset:0x3200
	ds_read_b64_tr_b16 v[246:247], v196 offset:0x3a00
	s_waitcnt lgkmcnt(0)
	v_mfma_f32_32x32x16_bf16 v[2:17], v[174:177], v[240:243], v[2:17]
	v_mfma_f32_32x32x16_bf16 v[50:65], v[166:169], v[190:193], v[50:65]
	ds_read_b64_tr_b16 v[190:191], v196 offset:0x400
	ds_read_b64_tr_b16 v[192:193], v196 offset:0xc00
	v_mfma_f32_32x32x16_bf16 v[50:65], v[162:165], v[232:235], v[50:65]
	ds_read_b64_tr_b16 v[232:233], v196 offset:0x1400
	ds_read_b64_tr_b16 v[234:235], v196 offset:0x1c00
	v_mfma_f32_32x32x16_bf16 v[50:65], v[170:173], v[236:239], v[50:65]
	ds_read_b64_tr_b16 v[236:237], v196 offset:0x2400
	ds_read_b64_tr_b16 v[238:239], v196 offset:0x2c00
	ds_read_b64_tr_b16 v[240:241], v196 offset:0x3400
	ds_read_b64_tr_b16 v[242:243], v196 offset:0x3c00
	s_waitcnt lgkmcnt(0)
	v_mfma_f32_32x32x16_bf16 v[50:65], v[174:177], v[244:247], v[50:65]
	v_mfma_f32_32x32x16_bf16 v[34:49], v[166:169], v[190:193], v[34:49]
	ds_read_b64_tr_b16 v[190:191], v196 offset:0x600
	ds_read_b64_tr_b16 v[192:193], v196 offset:0xe00
	v_mfma_f32_32x32x16_bf16 v[34:49], v[162:165], v[232:235], v[34:49]
	ds_read_b64_tr_b16 v[232:233], v196 offset:0x1600
	ds_read_b64_tr_b16 v[234:235], v196 offset:0x1e00
	v_mfma_f32_32x32x16_bf16 v[34:49], v[170:173], v[236:239], v[34:49]
	ds_read_b64_tr_b16 v[236:237], v196 offset:0x2600
	ds_read_b64_tr_b16 v[238:239], v196 offset:0x2e00
	ds_read_b64_tr_b16 v[244:245], v196 offset:0x3600
	ds_read_b64_tr_b16 v[246:247], v196 offset:0x3e00
	s_waitcnt lgkmcnt(0)
	v_mfma_f32_32x32x16_bf16 v[34:49], v[174:177], v[240:243], v[34:49]
	v_mfma_f32_32x32x16_bf16 v[18:33], v[166:169], v[190:193], v[18:33]
	v_max3_f32 v231, v82, v83, v84
	v_max3_f32 v240, v66, v67, v68
	s_nop 0
	v_max3_f32 v231, v231, v85, v86
	v_max3_f32 v240, v240, v69, v70
	v_max3_f32 v166, v240, v71, v72
	v_mfma_f32_32x32x16_bf16 v[18:33], v[162:165], v[232:235], v[18:33]
	v_max3_f32 v231, v231, v87, v88
	v_max3_f32 v166, v166, v73, v74
	v_max_f32_e32 v164, v81, v81
	v_max3_f32 v167, v231, v89, v90
	v_max3_f32 v166, v166, v75, v76
	v_max_f32_e32 v165, v97, v97
	v_max3_f32 v167, v167, v91, v92
	v_mfma_f32_32x32x16_bf16 v[18:33], v[170:173], v[236:239], v[18:33]
	v_max3_f32 v167, v167, v93, v94
	v_max3_f32 v166, v166, v77, v78
	v_max_f32_e32 v164, v165, v164
	v_max3_f32 v162, v167, v95, v96
	v_max3_f32 v163, v166, v79, v80
	s_nop 0
	v_max3_f32 v162, v162, v163, v164
	v_mfma_f32_32x32x16_bf16 v[18:33], v[174:177], v[244:247], v[18:33]
	v_mov_b32_e32 v163, v162
	s_nop 1
	v_permlane32_swap_b32_e32 v162, v163
	v_max_f32_e32 v163, v163, v163
	v_max_f32_e32 v162, v162, v162
	v_max_f32_e32 v162, v162, v163
	v_max_f32_e32 v163, v228, v228
	v_max_f32_e32 v163, v163, v162
	v_sub_f32_e32 v164, v162, v228
	v_sub_f32_e32 v162, v228, v163
	v_mul_f32_e32 v162, 0x3e0293ee, v162
	v_exp_f32_e32 v162, v162
	v_cmp_ge_f32_e32 vcc, s16, v164
	s_cmp_eq_u64 vcc, exec
	s_cselect_b64 s[6:7], -1, 0
	s_waitcnt vmcnt(4)
	v_cndmask_b32_e64 v162, v162, 1.0, s[6:7]
	v_cmp_gt_f32_e32 vcc, 1.0, v162
	s_bitcmp1_b32 s29, 10
	s_cbranch_scc1 .Lattn_xs2
	v_cndmask_b32_e64 v174, v163, v228, s[6:7]
	v_mul_f32_e32 v232, 0xbe0293ee, v174
	v_mov_b32_e32 v233, v232
	v_fmamk_f32 v82, v82, 0x3e0293ee, v232
	v_fmamk_f32 v83, v83, 0x3e0293ee, v232
	v_fmamk_f32 v84, v84, 0x3e0293ee, v232
	v_fmamk_f32 v85, v85, 0x3e0293ee, v232
	v_fmamk_f32 v86, v86, 0x3e0293ee, v232
	v_fmamk_f32 v87, v87, 0x3e0293ee, v232
	v_fmamk_f32 v88, v88, 0x3e0293ee, v232
	v_fmamk_f32 v89, v89, 0x3e0293ee, v232
	v_fmamk_f32 v90, v90, 0x3e0293ee, v232
	v_fmamk_f32 v91, v91, 0x3e0293ee, v232
	v_fmamk_f32 v92, v92, 0x3e0293ee, v232
	v_fmamk_f32 v93, v93, 0x3e0293ee, v232
	v_fmamk_f32 v94, v94, 0x3e0293ee, v232
	v_fmamk_f32 v95, v95, 0x3e0293ee, v232
	v_fmamk_f32 v96, v96, 0x3e0293ee, v232
	v_fmac_f32_e32 v233, 0x3e0293ee, v97
	v_exp_f32_e32 v177, v82
	v_exp_f32_e32 v191, v83
	v_exp_f32_e32 v163, v84
	v_exp_f32_e32 v190, v85
	v_exp_f32_e32 v164, v86
	v_exp_f32_e32 v176, v87
	v_exp_f32_e32 v165, v88
	v_exp_f32_e32 v175, v89
	v_exp_f32_e32 v166, v90
	v_exp_f32_e32 v173, v91
	v_exp_f32_e32 v167, v92
	v_exp_f32_e32 v172, v93
	v_exp_f32_e32 v168, v94
	v_exp_f32_e32 v170, v95
	v_exp_f32_e32 v169, v96
	v_exp_f32_e32 v171, v233
.Lattn_xs2:
	s_barrier
	s_cmp_eq_u64 s[38:39], 0
	s_cbranch_scc1 .Lattn_notlast
	s_waitcnt vmcnt(0)
.Lattn_notlast:
	ds_write_b128 v209, v[146:149] offset:16384
	ds_write_b128 v210, v[150:153] offset:16384
	ds_write_b128 v211, v[154:157] offset:49152
	ds_write_b128 v212, v[158:161] offset:49152
	s_cbranch_vccz .LBB0_528
	s_bitcmp1_b32 s29, 10
	s_cbranch_scc0 .Lattn_rescx2
	s_and_saveexec_b64 s[40:41], s[4:5]
	ds_write_b32 v222, v162 offset:128
	s_or_b64 exec, exec, s[40:41]
	s_waitcnt lgkmcnt(0)
	v_add_u32_e32 v158, s29, v195
	ds_read_b128 v[146:149], v158 offset:224
	ds_read_b128 v[150:153], v158 offset:192
	ds_read_b128 v[154:157], v158 offset:160
	ds_read_b128 v[158:161], v158 offset:128
	s_waitcnt lgkmcnt(3)
	v_pk_mul_f32 v[14:15], v[14:15], v[146:147]
	s_waitcnt lgkmcnt(2)
	v_pk_mul_f32 v[10:11], v[10:11], v[150:151]
	s_waitcnt lgkmcnt(1)
	v_pk_mul_f32 v[6:7], v[6:7], v[154:155]
	v_pk_mul_f32 v[16:17], v[16:17], v[148:149]
	v_pk_mul_f32 v[12:13], v[12:13], v[152:153]
	v_pk_mul_f32 v[8:9], v[8:9], v[156:157]
	s_waitcnt lgkmcnt(0)
	v_pk_mul_f32 v[4:5], v[4:5], v[160:161]
	v_pk_mul_f32 v[2:3], v[2:3], v[158:159]
	v_pk_mul_f32 v[62:63], v[62:63], v[146:147]
	v_pk_mul_f32 v[58:59], v[58:59], v[150:151]
	v_pk_mul_f32 v[54:55], v[54:55], v[154:155]
	v_pk_mul_f32 v[64:65], v[64:65], v[148:149]
	v_pk_mul_f32 v[60:61], v[60:61], v[152:153]
	v_pk_mul_f32 v[56:57], v[56:57], v[156:157]
	v_pk_mul_f32 v[52:53], v[52:53], v[160:161]
	v_pk_mul_f32 v[50:51], v[50:51], v[158:159]
	v_pk_mul_f32 v[46:47], v[46:47], v[146:147]
	v_pk_mul_f32 v[42:43], v[42:43], v[150:151]
	v_pk_mul_f32 v[38:39], v[38:39], v[154:155]
	v_pk_mul_f32 v[48:49], v[48:49], v[148:149]
	v_pk_mul_f32 v[44:45], v[44:45], v[152:153]
	v_pk_mul_f32 v[40:41], v[40:41], v[156:157]
	v_pk_mul_f32 v[36:37], v[36:37], v[160:161]
	v_pk_mul_f32 v[34:35], v[34:35], v[158:159]
	v_pk_mul_f32 v[30:31], v[30:31], v[146:147]
	v_pk_mul_f32 v[26:27], v[26:27], v[150:151]
	v_pk_mul_f32 v[22:23], v[22:23], v[154:155]
	v_pk_mul_f32 v[32:33], v[32:33], v[148:149]
	v_pk_mul_f32 v[28:29], v[28:29], v[152:153]
	v_pk_mul_f32 v[24:25], v[24:25], v[156:157]
	v_pk_mul_f32 v[20:21], v[20:21], v[160:161]
	v_pk_mul_f32 v[18:19], v[18:19], v[158:159]
.LBB0_528:
	s_bitcmp1_b32 s29, 10
	s_cbranch_scc1 .Lattn_ysk2
	v_mul_f32_e32 v148, 0xbe0293ee, v174
	v_pk_fma_f32 v[158:159], v[66:67], s[12:13], v[148:149] op_sel_hi:[1,0,0]
	v_add_f32_e32 v66, v225, v226
	v_fmac_f32_e32 v66, v224, v223
	v_add_f32_e32 v223, v229, v230
	v_pk_fma_f32 v[156:157], v[68:69], s[12:13], v[148:149] op_sel_hi:[1,0,0]
	v_pk_fma_f32 v[152:153], v[70:71], s[12:13], v[148:149] op_sel_hi:[1,0,0]
	v_pk_fma_f32 v[150:151], v[72:73], s[12:13], v[148:149] op_sel_hi:[1,0,0]
	v_pk_fma_f32 v[146:147], v[74:75], s[12:13], v[148:149] op_sel_hi:[1,0,0]
	v_pk_fma_f32 v[160:161], v[76:77], s[12:13], v[148:149] op_sel_hi:[1,0,0]
	v_pk_fma_f32 v[154:155], v[78:79], s[12:13], v[148:149] op_sel_hi:[1,0,0]
	v_pk_fma_f32 v[148:149], v[80:81], s[12:13], v[148:149] op_sel_hi:[1,0,0]
	v_fmac_f32_e32 v223, v66, v227
	v_lshl_add_u64 v[186:187], v[186:187], 0, s[64:65]
	v_lshl_add_u64 v[188:189], v[188:189], 0, s[64:65]
.Lattn_ysk2:
	s_add_i32 s30, s30, 2
	s_and_b64 vcc, exec, s[38:39]
	s_waitcnt lgkmcnt(0)
	s_barrier
	s_bitcmp1_b32 s29, 10
	s_cbranch_scc0 .Lattn_ys2
	v_cndmask_b32_e64 v174, v163, v228, s[6:7]
	v_mul_f32_e32 v148, 0xbe0293ee, v174
	v_mov_b32_e32 v149, v148
	v_fmamk_f32 v82, v82, 0x3e0293ee, v148
	v_fmamk_f32 v83, v83, 0x3e0293ee, v148
	v_fmamk_f32 v84, v84, 0x3e0293ee, v148
	v_fmamk_f32 v85, v85, 0x3e0293ee, v148
	v_fmamk_f32 v86, v86, 0x3e0293ee, v148
	v_fmamk_f32 v87, v87, 0x3e0293ee, v148
	v_fmamk_f32 v88, v88, 0x3e0293ee, v148
	v_fmamk_f32 v89, v89, 0x3e0293ee, v148
	v_fmamk_f32 v90, v90, 0x3e0293ee, v148
	v_fmamk_f32 v91, v91, 0x3e0293ee, v148
	v_fmamk_f32 v92, v92, 0x3e0293ee, v148
	v_fmamk_f32 v93, v93, 0x3e0293ee, v148
	v_fmamk_f32 v94, v94, 0x3e0293ee, v148
	v_fmamk_f32 v95, v95, 0x3e0293ee, v148
	v_fmamk_f32 v96, v96, 0x3e0293ee, v148
	v_fmac_f32_e32 v149, 0x3e0293ee, v97
	v_exp_f32_e32 v177, v82
	v_exp_f32_e32 v191, v83
	v_exp_f32_e32 v163, v84
	v_exp_f32_e32 v190, v85
	v_exp_f32_e32 v164, v86
	v_exp_f32_e32 v176, v87
	v_exp_f32_e32 v165, v88
	v_exp_f32_e32 v175, v89
	v_exp_f32_e32 v166, v90
	v_exp_f32_e32 v173, v91
	v_exp_f32_e32 v167, v92
	v_exp_f32_e32 v172, v93
	v_exp_f32_e32 v168, v94
	v_exp_f32_e32 v170, v95
	v_exp_f32_e32 v169, v96
	v_exp_f32_e32 v171, v149
	v_pk_fma_f32 v[158:159], v[66:67], s[12:13], v[148:149] op_sel_hi:[1,0,0]
	v_add_f32_e32 v66, v225, v226
	v_fmac_f32_e32 v66, v224, v223
	v_add_f32_e32 v223, v229, v230
	v_pk_fma_f32 v[156:157], v[68:69], s[12:13], v[148:149] op_sel_hi:[1,0,0]
	v_pk_fma_f32 v[152:153], v[70:71], s[12:13], v[148:149] op_sel_hi:[1,0,0]
	v_pk_fma_f32 v[150:151], v[72:73], s[12:13], v[148:149] op_sel_hi:[1,0,0]
	v_pk_fma_f32 v[146:147], v[74:75], s[12:13], v[148:149] op_sel_hi:[1,0,0]
	v_pk_fma_f32 v[160:161], v[76:77], s[12:13], v[148:149] op_sel_hi:[1,0,0]
	v_pk_fma_f32 v[154:155], v[78:79], s[12:13], v[148:149] op_sel_hi:[1,0,0]
	v_pk_fma_f32 v[148:149], v[80:81], s[12:13], v[148:149] op_sel_hi:[1,0,0]
	v_fmac_f32_e32 v223, v66, v227
	v_lshl_add_u64 v[186:187], v[186:187], 0, s[64:65]
	v_lshl_add_u64 v[188:189], v[188:189], 0, s[64:65]
.Lattn_ys2:
	s_cbranch_vccnz .LBB0_530
	v_mov_b32_e32 v224, v162
	s_branch .LBB0_518
.Lattn_rescx1:
	s_and_saveexec_b64 s[38:39], s[4:5]
	ds_write_b32 v222, v227 offset:128
	s_or_b64 exec, exec, s[38:39]
	s_waitcnt lgkmcnt(0)
	v_add_u32_e32 v82, s29, v195
	ds_read_b128 v[66:69], v82 offset:224
	ds_read_b128 v[70:73], v82 offset:192
	ds_read_b128 v[74:77], v82 offset:160
	ds_read_b128 v[78:81], v82 offset:128
	s_waitcnt lgkmcnt(3)
	v_pk_mul_f32 v[14:15], v[14:15], v[66:67]
	s_waitcnt lgkmcnt(2)
	v_pk_mul_f32 v[10:11], v[10:11], v[70:71]
	s_waitcnt lgkmcnt(1)
	v_pk_mul_f32 v[6:7], v[6:7], v[74:75]
	v_pk_mul_f32 v[16:17], v[16:17], v[68:69]
	v_pk_mul_f32 v[12:13], v[12:13], v[72:73]
	v_pk_mul_f32 v[8:9], v[8:9], v[76:77]
	s_waitcnt lgkmcnt(0)
	v_pk_mul_f32 v[4:5], v[4:5], v[80:81]
	v_pk_mul_f32 v[2:3], v[2:3], v[78:79]
	v_pk_mul_f32 v[62:63], v[62:63], v[66:67]
	v_pk_mul_f32 v[58:59], v[58:59], v[70:71]
	v_pk_mul_f32 v[54:55], v[54:55], v[74:75]
	v_pk_mul_f32 v[64:65], v[64:65], v[68:69]
	v_pk_mul_f32 v[60:61], v[60:61], v[72:73]
	v_pk_mul_f32 v[56:57], v[56:57], v[76:77]
	v_pk_mul_f32 v[52:53], v[52:53], v[80:81]
	v_pk_mul_f32 v[50:51], v[50:51], v[78:79]
	v_pk_mul_f32 v[46:47], v[46:47], v[66:67]
	v_pk_mul_f32 v[42:43], v[42:43], v[70:71]
	v_pk_mul_f32 v[38:39], v[38:39], v[74:75]
	v_pk_mul_f32 v[48:49], v[48:49], v[68:69]
	v_pk_mul_f32 v[44:45], v[44:45], v[72:73]
	v_pk_mul_f32 v[40:41], v[40:41], v[76:77]
	v_pk_mul_f32 v[36:37], v[36:37], v[80:81]
	v_pk_mul_f32 v[34:35], v[34:35], v[78:79]
	v_pk_mul_f32 v[30:31], v[30:31], v[66:67]
	v_pk_mul_f32 v[26:27], v[26:27], v[70:71]
	v_pk_mul_f32 v[22:23], v[22:23], v[74:75]
	v_pk_mul_f32 v[32:33], v[32:33], v[68:69]
	v_pk_mul_f32 v[28:29], v[28:29], v[72:73]
	v_pk_mul_f32 v[24:25], v[24:25], v[76:77]
	v_pk_mul_f32 v[20:21], v[20:21], v[80:81]
	v_pk_mul_f32 v[18:19], v[18:19], v[78:79]
	s_branch .LBB0_522
.Lattn_rescx2:
	s_and_saveexec_b64 s[40:41], s[4:5]
	ds_write_b32 v222, v162 offset:128
	s_or_b64 exec, exec, s[40:41]
	s_waitcnt lgkmcnt(0)
	v_add_u32_e32 v232, s29, v195
	ds_read_b128 v[82:85], v232 offset:224
	ds_read_b128 v[86:89], v232 offset:192
	ds_read_b128 v[90:93], v232 offset:160
	ds_read_b128 v[94:97], v232 offset:128
	s_waitcnt lgkmcnt(3)
	v_pk_mul_f32 v[14:15], v[14:15], v[82:83]
	s_waitcnt lgkmcnt(2)
	v_pk_mul_f32 v[10:11], v[10:11], v[86:87]
	s_waitcnt lgkmcnt(1)
	v_pk_mul_f32 v[6:7], v[6:7], v[90:91]
	v_pk_mul_f32 v[16:17], v[16:17], v[84:85]
	v_pk_mul_f32 v[12:13], v[12:13], v[88:89]
	v_pk_mul_f32 v[8:9], v[8:9], v[92:93]
	s_waitcnt lgkmcnt(0)
	v_pk_mul_f32 v[4:5], v[4:5], v[96:97]
	v_pk_mul_f32 v[2:3], v[2:3], v[94:95]
	v_pk_mul_f32 v[62:63], v[62:63], v[82:83]
	v_pk_mul_f32 v[58:59], v[58:59], v[86:87]
	v_pk_mul_f32 v[54:55], v[54:55], v[90:91]
	v_pk_mul_f32 v[64:65], v[64:65], v[84:85]
	v_pk_mul_f32 v[60:61], v[60:61], v[88:89]
	v_pk_mul_f32 v[56:57], v[56:57], v[92:93]
	v_pk_mul_f32 v[52:53], v[52:53], v[96:97]
	v_pk_mul_f32 v[50:51], v[50:51], v[94:95]
	v_pk_mul_f32 v[46:47], v[46:47], v[82:83]
	v_pk_mul_f32 v[42:43], v[42:43], v[86:87]
	v_pk_mul_f32 v[38:39], v[38:39], v[90:91]
	v_pk_mul_f32 v[48:49], v[48:49], v[84:85]
	v_pk_mul_f32 v[44:45], v[44:45], v[88:89]
	v_pk_mul_f32 v[40:41], v[40:41], v[92:93]
	v_pk_mul_f32 v[36:37], v[36:37], v[96:97]
	v_pk_mul_f32 v[34:35], v[34:35], v[94:95]
	v_pk_mul_f32 v[30:31], v[30:31], v[82:83]
	v_pk_mul_f32 v[26:27], v[26:27], v[86:87]
	v_pk_mul_f32 v[22:23], v[22:23], v[90:91]
	v_pk_mul_f32 v[32:33], v[32:33], v[84:85]
	v_pk_mul_f32 v[28:29], v[28:29], v[88:89]
	v_pk_mul_f32 v[24:25], v[24:25], v[92:93]
	v_pk_mul_f32 v[20:21], v[20:21], v[96:97]
	v_pk_mul_f32 v[18:19], v[18:19], v[94:95]
	s_branch .LBB0_528
